# v46 + mLSTM S9: LDS operand reads for the 24 MFMAs issued two k-steps ahead into spare VGPRs with counted waits (was 16 serial read-wait-MFMA round trips)
# speedup vs baseline: 1.0070x; 1.0047x over previous
; #define LAS __attribute__((address_space(3)))
; __device__ __forceinline__ float bflo(unsigned u) { return __uint_as_float(u << 16); }
; __device__ __forceinline__ void mlstm_item(const P& p, const Ctx& c, int seg, int w, bool save) {
;     ...
;             { const int tm = c.wv >> 1, tn0 = (c.wv & 1) * 2;
; #pragma unroll
;               for (int kk = 0; kk < 4; ++kk) { const bf16x8 a = *(const LAS bf16x8*)(Qs + (tm * 16 + l15) * 136 + kk * 32 + quad * 8);
; #pragma unroll
;                   for (int x = 0; x < 2; ++x) { const int tn = tn0 + x;
;                       const bf16x8 bk = *(const LAS bf16x8*)(Ks + (tn * 16 + l15) * 136 + kk * 32 + quad * 8);
;                       const bf16x8 bc = *(const LAS bf16x8*)(Cimg + (tn * 16 + l15) * 392 + d0 + kk * 32 + quad * 8);
;                       Sa[x] = mfma16(a, bk, Sa[x]); Ia[x] = mfma16(a, bc, Ia[x]); } } }
;             { const bf16x8 va0 = *(const LAS bf16x8*)(VWs + (e16 * 16 + l15) * 72 + quad * 8), va1 = *(const LAS bf16x8*)(VWs + (e16 * 16 + l15) * 72 + 32 + quad * 8);
; #pragma unroll
;               for (int jl = 0; jl < 4; ++jl) { const int ntl = 2 * jl + par, j = pp * 4 + jl;
;                   C[j] = mfma16(va0, *(const LAS bf16x8*)(KTs + (ntl * 16 + l15) * 72 + quad * 8), C[j]);
;                   C[j] = mfma16(va1, *(const LAS bf16x8*)(KTs + (ntl * 16 + l15) * 72 + 32 + quad * 8), C[j]); } }
;             { const int t = tidv >> 3, part = tidv & 7;
;               const u32x4 q0 = *(const LAS u32x4*)(Qs + t * 136 + part * 16), q1 = *(const LAS u32x4*)(Qs + t * 136 + part * 16 + 8);
;               const LAS float* np = nold + d0 + part * 16; const f32x4 n0 = *(const LAS f32x4*)np, n1 = *(const LAS f32x4*)(np + 4), n2 = *(const LAS f32x4*)(np + 8), n3 = *(const LAS f32x4*)(np + 12);
;               qnacc += bflo(q0.x) * n0[0] + bfhi(q0.x) * n0[1] + bflo(q0.y) * n0[2] + bfhi(q0.y) * n0[3] + bflo(q0.z) * n1[0] + bfhi(q0.z) * n1[1] + bflo(q0.w) * n1[2] + bfhi(q0.w) * n1[3]
;                      + bflo(q1.x) * n2[0] + bfhi(q1.x) * n2[1] + bflo(q1.y) * n2[2] + bfhi(q1.y) * n2[3] + bflo(q1.z) * n3[0] + bfhi(q1.z) * n3[1] + bflo(q1.w) * n3[2] + bfhi(q1.w) * n3[3]; }
;             { const int dd = tidv >> 2, part = tidv & 3;
;               const u32x4 k0 = *(const LAS u32x4*)(KTs + dd * 72 + part * 16), k1 = *(const LAS u32x4*)(KTs + dd * 72 + part * 16 + 8);
.LBB0_379:
	v_mov_b32_e32 v146, v182
	v_mov_b32_e32 v147, v182
	v_pk_mul_f32 v[40:41], v[40:41], v[146:147]
	v_pk_mul_f32 v[44:45], v[44:45], v[146:147]
	v_pk_mul_f32 v[48:49], v[48:49], v[146:147]
	v_pk_mul_f32 v[56:57], v[56:57], v[146:147]
	ds_read_b128 v[146:149], v157 offset:50176
	ds_read_b128 v[160:163], v158
	ds_read_b128 v[164:167], v155 offset:512
	ds_read_b128 v[208:211], v156
	ds_read_b128 v[218:221], v153 offset:512
	ds_read_b128 v[234:237], v157 offset:50240
	ds_read_b128 v[238:241], v158 offset:64
	ds_read_b128 v[242:245], v155 offset:576
	ds_read_b128 v[246:249], v156 offset:64
	ds_read_b128 v[250:253], v153 offset:576
	v_mul_f32_e64 v38, v38, v182
	v_mul_f32_e64 v39, v39, v183
	v_pk_mul_f32 v[42:43], v[42:43], v[182:183]
	v_pk_mul_f32 v[46:47], v[46:47], v[182:183]
	v_pk_mul_f32 v[54:55], v[54:55], v[182:183]
	v_mul_lo_u32 v4, v184, s38
	v_and_b32_e32 v172, 3, v191
	v_lshlrev_b32_e32 v183, 5, v172
	v_cmp_eq_u32_e32 vcc, 0, v172
	s_waitcnt lgkmcnt(8)
	v_mfma_f32_16x16x32_bf16 v[130:133], v[146:149], v[160:163], v[130:133]
	s_waitcnt lgkmcnt(7)
	v_mfma_f32_16x16x32_bf16 v[134:137], v[146:149], v[164:167], v[134:137]
	s_waitcnt lgkmcnt(6)
	v_mfma_f32_16x16x32_bf16 v[138:141], v[146:149], v[208:211], v[138:141]
	s_waitcnt lgkmcnt(5)
	v_mfma_f32_16x16x32_bf16 v[142:145], v[146:149], v[218:221], v[142:145]
	ds_read_b128 v[146:149], v157 offset:50304
	ds_read_b128 v[160:163], v158 offset:128
	ds_read_b128 v[164:167], v155 offset:640
	ds_read_b128 v[208:211], v156 offset:128
	ds_read_b128 v[218:221], v153 offset:640
	s_waitcnt lgkmcnt(8)
	v_mfma_f32_16x16x32_bf16 v[130:133], v[234:237], v[238:241], v[130:133]
	s_waitcnt lgkmcnt(7)
	v_mfma_f32_16x16x32_bf16 v[134:137], v[234:237], v[242:245], v[134:137]
	s_waitcnt lgkmcnt(6)
	v_mfma_f32_16x16x32_bf16 v[138:141], v[234:237], v[246:249], v[138:141]
	s_waitcnt lgkmcnt(5)
	v_mfma_f32_16x16x32_bf16 v[142:145], v[234:237], v[250:253], v[142:145]
	ds_read_b128 v[234:237], v157 offset:50368
	ds_read_b128 v[238:241], v158 offset:192
	ds_read_b128 v[242:245], v155 offset:704
	ds_read_b128 v[246:249], v156 offset:192
	ds_read_b128 v[250:253], v153 offset:704
	s_waitcnt lgkmcnt(8)
	v_mfma_f32_16x16x32_bf16 v[130:133], v[146:149], v[160:163], v[130:133]
	s_waitcnt lgkmcnt(7)
	v_mfma_f32_16x16x32_bf16 v[134:137], v[146:149], v[164:167], v[134:137]
	s_waitcnt lgkmcnt(6)
	v_mfma_f32_16x16x32_bf16 v[138:141], v[146:149], v[208:211], v[138:141]
	s_waitcnt lgkmcnt(5)
	v_mfma_f32_16x16x32_bf16 v[146:149], v[146:149], v[218:221], v[142:145]
	ds_read_b128 v[160:163], v152
	ds_read_b128 v[150:153], v152 offset:64
	ds_read_b128 v[164:167], v154
	ds_read_b128 v[208:211], v154 offset:64
	ds_read_b128 v[218:221], v154 offset:4608
	ds_read_b128 v[156:159], v154 offset:4672
	s_waitcnt lgkmcnt(9)
	v_mfma_f32_16x16x32_bf16 v[142:145], v[234:237], v[238:241], v[130:133]
	s_waitcnt lgkmcnt(8)
	v_mfma_f32_16x16x32_bf16 v[130:133], v[234:237], v[242:245], v[134:137]
	s_waitcnt lgkmcnt(7)
	v_mfma_f32_16x16x32_bf16 v[138:141], v[234:237], v[246:249], v[138:141]
	s_waitcnt lgkmcnt(6)
	v_mfma_f32_16x16x32_bf16 v[134:137], v[234:237], v[250:253], v[146:149]
	ds_read_b128 v[238:241], v154 offset:9216
	ds_read_b128 v[242:245], v154 offset:9280
	ds_read_b128 v[246:249], v154 offset:13824
	ds_read_b128 v[250:253], v154 offset:13888
	s_waitcnt lgkmcnt(7)
	v_mfma_f32_16x16x32_bf16 v[38:41], v[160:163], v[164:167], v[38:41]
	s_waitcnt lgkmcnt(5)
	v_mfma_f32_16x16x32_bf16 v[42:45], v[160:163], v[218:221], v[42:45]
	v_mfma_f32_16x16x32_bf16 v[38:41], v[150:153], v[208:211], v[38:41]
	s_waitcnt lgkmcnt(4)
	v_mfma_f32_16x16x32_bf16 v[42:45], v[150:153], v[156:159], v[42:45]
	s_waitcnt lgkmcnt(3)
	v_mfma_f32_16x16x32_bf16 v[46:49], v[160:163], v[238:241], v[46:49]
	s_waitcnt lgkmcnt(1)
	v_mfma_f32_16x16x32_bf16 v[54:57], v[160:163], v[246:249], v[54:57]
	v_mfma_f32_16x16x32_bf16 v[46:49], v[150:153], v[242:245], v[46:49]
	s_waitcnt lgkmcnt(0)
	v_mfma_f32_16x16x32_bf16 v[54:57], v[150:153], v[250:253], v[54:57]
	v_lshlrev_b32_e32 v146, 4, v191
	v_and_b32_e32 v150, 0x70, v146
	v_lshlrev_b32_e32 v146, 1, v150
	v_add3_u32 v4, 0, v4, v146
	ds_read_b128 v[154:157], v4 offset:50176
	ds_read_b128 v[146:149], v4 offset:50192
	v_lshl_add_u32 v4, v150, 2, 0
	v_add_u32_e32 v4, 0x20a40, v4
	ds_read_b128 v[166:169], v4
	ds_read_b128 v[162:165], v4 offset:16
	ds_read_b128 v[158:161], v4 offset:32
	ds_read_b128 v[150:153], v4 offset:48
	v_ashrrev_i32_e32 v4, 2, v191
	v_mul_lo_u32 v173, v4, s63
	v_add3_u32 v173, s18, v173, v183
	ds_read_b128 v[196:199], v173
	ds_read_b128 v[200:203], v173 offset:16
	v_lshl_add_u32 v173, v172, 6, 0
	v_add_u32_e32 v173, 0x20200, v173
	ds_read_b128 v[204:207], v173
	ds_read_b128 v[222:225], v173 offset:16
	ds_read_b128 v[226:229], v173 offset:32
	ds_read_b128 v[230:233], v173 offset:48
	s_waitcnt lgkmcnt(5)
	v_and_b32_e32 v183, 0xffff0000, v196
	v_lshlrev_b32_e32 v173, 16, v196
	s_waitcnt lgkmcnt(3)
	v_mul_f32_e32 v183, v205, v183
	v_fmac_f32_e32 v183, v204, v173
	v_lshlrev_b32_e32 v173, 16, v197
	v_fmac_f32_e32 v183, v206, v173
	v_and_b32_e32 v173, 0xffff0000, v197
	v_fmac_f32_e32 v183, v207, v173
	v_lshlrev_b32_e32 v173, 16, v198
	s_waitcnt lgkmcnt(2)
	v_fmac_f32_e32 v183, v222, v173
	v_and_b32_e32 v173, 0xffff0000, v198
	v_fmac_f32_e32 v183, v223, v173
	v_lshlrev_b32_e32 v173, 16, v199
	v_fmac_f32_e32 v183, v224, v173
	v_and_b32_e32 v173, 0xffff0000, v199
	v_fmac_f32_e32 v183, v225, v173
	v_lshlrev_b32_e32 v173, 16, v200
	s_waitcnt lgkmcnt(1)
	v_fmac_f32_e32 v183, v226, v173
	v_and_b32_e32 v173, 0xffff0000, v200
	v_fmac_f32_e32 v183, v227, v173
	v_lshlrev_b32_e32 v173, 16, v201
	v_fmac_f32_e32 v183, v228, v173
	v_and_b32_e32 v173, 0xffff0000, v201
	v_fmac_f32_e32 v183, v229, v173
	v_lshlrev_b32_e32 v173, 16, v202
	s_waitcnt lgkmcnt(0)
	v_fmac_f32_e32 v183, v230, v173
	v_and_b32_e32 v173, 0xffff0000, v202
	v_fmac_f32_e32 v183, v231, v173
	v_lshlrev_b32_e32 v173, 16, v203
	v_fmac_f32_e32 v183, v232, v173
	v_and_b32_e32 v173, 0xffff0000, v203
	v_fmac_f32_e32 v183, v233, v173
	s_nop 1
	v_add_f32_dpp v183, v183, v183 quad_perm:[1,0,3,2] row_mask:0xf bank_mask:0xf bound_ctrl:1
	s_nop 1
	v_mov_b32_dpp v185, v183 quad_perm:[2,3,0,1] row_mask:0xf bank_mask:0xf bound_ctrl:1
	s_and_saveexec_b64 s[16:17], vcc
	s_cbranch_execz .LBB0_381
	v_lshl_add_u32 v4, v4, 2, 0
	v_add_u32_e32 v173, 0x20a40, v4
	ds_read_b32 v173, v173
	v_add_f32_e32 v172, v183, v185
	v_add_u32_e32 v4, 0x21080, v4
	s_waitcnt lgkmcnt(0)
	v_fmac_f32_e32 v172, v182, v173
	ds_write_b32 v4, v172
